# shortened wave-uniform rescale test in attention loops (v_cmp + s_cbranch_vccz instead of cmp/cselect/andn2 chain), 4 sites
# speedup vs baseline: 1.0030x; 1.0030x over previous
; #define LAS __attribute__((address_space(3)))
; __device__ __forceinline__ int crow(int r, int hi) { return (r & 3) + 8 * (r >> 2) + 4 * hi; }
; template <int DQK, int DV, bool HAS_BIAS>
; __device__ __forceinline__ void attn_tile(AttnState<DQK, DV>& st, const LAS unsigned char* Kt, const LAS unsigned char* Vt, int bias_mode, const LAS float* tab, int rel0, int nkeys, bool first, LAS float* wsf, int lane) {
;     ...
; #pragma unroll
;     for (int ks = 1; ks < KS; ++ks) {
;         p0 = __builtin_amdgcn_mfma_f32_32x32x16_bf16(ka[ks], st.qf[ks], p0, 0, 0, 0);
;         p1 = __builtin_amdgcn_mfma_f32_32x32x16_bf16(kb[ks], st.qf[ks], p1, 0, 0, 0);
;     }
;     const int q4 = (lane & 15) >> 2, blk = (lane >> 4) & 1, pp = lane & 3;
;     const LAS unsigned char* vp = Vt + (4 * hi + q4) * PV + (16 * blk + 4 * pp) * 2;
;     s16x4 vlo[2][4], vhi[2][4];
; #pragma unroll
;     for (int s4 = 0; s4 < 4; ++s4) { vlo[0][s4] = vtr(vp + (16 * s4) * PV); vhi[0][s4] = vtr(vp + (16 * s4 + 8) * PV); }
;     __builtin_amdgcn_sched_barrier(0);
;     if (nkeys < 64) {
; #pragma unroll
;         for (int r = 0; r < 16; ++r) { const int k = crow(r, hi); if (k >= nkeys) p0[r] = -1e30f; if (k + 32 >= nkeys) p1[r] = -1e30f; }
;     }
;     float mxa = __builtin_fmaxf(__builtin_fmaxf(p0[0], p0[1]), p1[0]), mxb = __builtin_fmaxf(__builtin_fmaxf(p0[2], p0[3]), p1[1]);
;     mxa = __builtin_fmaxf(__builtin_fmaxf(mxa, p1[2]), p1[3]);
; #pragma unroll
;     for (int r = 4; r < 16; r += 4) {
;         mxa = __builtin_fmaxf(__builtin_fmaxf(mxa, p0[r]), p0[r + 1]); mxb = __builtin_fmaxf(__builtin_fmaxf(mxb, p0[r + 2]), p0[r + 3]);
;         mxa = __builtin_fmaxf(__builtin_fmaxf(mxa, p1[r]), p1[r + 1]); mxb = __builtin_fmaxf(__builtin_fmaxf(mxb, p1[r + 2]), p1[r + 3]);
;     }
;     const float mx = xmax32(__builtin_fmaxf(mxa, mxb));
;     if (first || __any(mx > ATT_THR)) {
;         const float dl = first ? mx : __builtin_fmaxf(mx, 0.f);
;         st.m += dl;
; #pragma unroll
;         for (int r = 0; r < 16; ++r) { st.negm[r] = -st.m; p0[r] -= dl; p1[r] -= dl; }
;         const float f = __builtin_amdgcn_exp2f(-dl);
;         st.l *= f;
;         if (hi == 0) wsf[q] = f;
; #pragma unroll
;         for (int r = 0; r < 16; ++r) { const float fr = wsf[crow(r, hi)];
; #pragma unroll
;             for (int db = 0; db < NDB; ++db) st.o[db][r] *= fr; }
;     }
.LBB0_527:
	s_waitcnt vmcnt(5) lgkmcnt(6)
	v_mfma_f32_32x32x16_bf16 v[80:95], v[160:163], v[116:119], v[80:95]
	s_cmp_eq_u32 s58, 0
	s_cselect_b64 s[2:3], -1, 0
	s_cmp_lg_u32 s58, 0
	s_waitcnt lgkmcnt(4)
	v_mfma_f32_32x32x16_bf16 v[96:111], v[164:167], v[116:119], v[96:111]
	s_waitcnt vmcnt(4) lgkmcnt(3)
	v_mfma_f32_32x32x16_bf16 v[80:95], v[156:159], v[120:123], v[80:95]
	s_waitcnt lgkmcnt(1)
	v_mfma_f32_32x32x16_bf16 v[96:111], v[172:175], v[120:123], v[96:111]
	s_waitcnt vmcnt(3)
	v_mfma_f32_32x32x16_bf16 v[80:95], v[152:155], v[124:127], v[80:95]
	ds_read_b64_tr_b16 v[152:153], v217 offset:17408
	ds_read_b64_tr_b16 v[154:155], v217 offset:19968
	ds_read_b64_tr_b16 v[156:157], v217 offset:17472
	ds_read_b64_tr_b16 v[158:159], v217 offset:20032
	ds_read_b64_tr_b16 v[160:161], v217 offset:17536
	ds_read_b64_tr_b16 v[162:163], v217 offset:20096
	ds_read_b64_tr_b16 v[164:165], v217 offset:17600
	ds_read_b64_tr_b16 v[166:167], v217 offset:20160
	s_waitcnt lgkmcnt(8)
	v_mfma_f32_32x32x16_bf16 v[96:111], v[168:171], v[124:127], v[96:111]
	ds_read_b64_tr_b16 v[226:227], v217 offset:22528
	ds_read_b64_tr_b16 v[228:229], v217 offset:25088
	ds_read_b64_tr_b16 v[230:231], v217 offset:22592
	ds_read_b64_tr_b16 v[232:233], v217 offset:25152
	ds_read_b64_tr_b16 v[234:235], v217 offset:22656
	ds_read_b64_tr_b16 v[236:237], v217 offset:25216
	ds_read_b64_tr_b16 v[238:239], v217 offset:22720
	ds_read_b64_tr_b16 v[240:241], v217 offset:25280
	s_nop 1
	v_max_f32_e32 v168, v81, v81
	v_max_f32_e32 v169, v80, v80
	v_max_f32_e32 v168, v169, v168
	s_nop 6
	v_max3_f32 v169, v82, v83, v97
	v_max3_f32 v168, v168, v96, v98
	v_max3_f32 v168, v168, v99, v84
	v_max3_f32 v169, v169, v86, v87
	v_max3_f32 v168, v168, v85, v100
	v_max3_f32 v169, v169, v102, v103
	v_max3_f32 v168, v168, v101, v88
	v_max3_f32 v169, v169, v90, v91
	v_max3_f32 v168, v168, v89, v104
	v_max3_f32 v169, v169, v106, v107
	v_max3_f32 v168, v168, v105, v92
	v_max3_f32 v169, v169, v94, v95
	v_max3_f32 v168, v168, v93, v108
	v_max3_f32 v169, v169, v110, v111
	v_max3_f32 v168, v168, v109, v169
	v_mov_b32_e32 v169, v168
	s_nop 1
	v_permlane32_swap_b32_e32 v168, v169
	v_max_f32_e32 v169, v169, v169
	v_max_f32_e32 v168, v168, v168
	v_max_f32_e32 v168, v168, v169
	s_cbranch_scc0 .Lresc_1
	v_cmp_lt_f32_e32 vcc, s77, v168
	s_cbranch_vccz .LBB0_535
.Lresc_1:
	v_max_f32_e32 v64, v168, v168
	v_max_f32_e32 v64, 0, v64
	v_cndmask_b32_e64 v168, v64, v168, s[2:3]
	v_exp_f32_e64 v169, -v168
	s_and_saveexec_b64 s[2:3], s[0:1]
	ds_write_b32 v216, v169 offset:6144
	s_or_b64 exec, exec, s[2:3]
	v_add_f32_e32 v220, v220, v168
	v_pk_add_f32 v[80:81], v[80:81], v[168:169] op_sel_hi:[1,0] neg_lo:[0,1] neg_hi:[0,1]
	v_pk_add_f32 v[96:97], v[96:97], v[168:169] op_sel_hi:[1,0] neg_lo:[0,1] neg_hi:[0,1]
	v_pk_add_f32 v[82:83], v[82:83], v[168:169] op_sel_hi:[1,0] neg_lo:[0,1] neg_hi:[0,1]
	v_pk_add_f32 v[98:99], v[98:99], v[168:169] op_sel_hi:[1,0] neg_lo:[0,1] neg_hi:[0,1]
	v_pk_add_f32 v[84:85], v[84:85], v[168:169] op_sel_hi:[1,0] neg_lo:[0,1] neg_hi:[0,1]
	v_pk_add_f32 v[100:101], v[100:101], v[168:169] op_sel_hi:[1,0] neg_lo:[0,1] neg_hi:[0,1]
	v_pk_add_f32 v[86:87], v[86:87], v[168:169] op_sel_hi:[1,0] neg_lo:[0,1] neg_hi:[0,1]
	v_pk_add_f32 v[102:103], v[102:103], v[168:169] op_sel_hi:[1,0] neg_lo:[0,1] neg_hi:[0,1]
	v_pk_add_f32 v[88:89], v[88:89], v[168:169] op_sel_hi:[1,0] neg_lo:[0,1] neg_hi:[0,1]
	v_pk_add_f32 v[104:105], v[104:105], v[168:169] op_sel_hi:[1,0] neg_lo:[0,1] neg_hi:[0,1]
	v_pk_add_f32 v[90:91], v[90:91], v[168:169] op_sel_hi:[1,0] neg_lo:[0,1] neg_hi:[0,1]
	v_pk_add_f32 v[106:107], v[106:107], v[168:169] op_sel_hi:[1,0] neg_lo:[0,1] neg_hi:[0,1]
	v_pk_add_f32 v[92:93], v[92:93], v[168:169] op_sel_hi:[1,0] neg_lo:[0,1] neg_hi:[0,1]
	v_pk_add_f32 v[108:109], v[108:109], v[168:169] op_sel_hi:[1,0] neg_lo:[0,1] neg_hi:[0,1]
	v_pk_add_f32 v[94:95], v[94:95], v[168:169] op_sel_hi:[1,0] neg_lo:[0,1] neg_hi:[0,1]
	v_pk_add_f32 v[110:111], v[110:111], v[168:169] op_sel_hi:[1,0] neg_lo:[0,1] neg_hi:[0,1]
	v_mul_f32_e32 v184, v184, v169
	ds_read_b128 v[168:171], v213 offset:6144
	ds_read_b128 v[172:175], v213 offset:6176
	ds_read_b128 v[176:179], v213 offset:6208
	ds_read_b128 v[180:183], v213 offset:6240
	v_xor_b32_e32 v64, 0x80000000, v220
	v_mov_b32_e32 v65, v64
	v_mov_b32_e32 v66, v64
	v_mov_b32_e32 v67, v64
	v_mov_b32_e32 v68, v64
	v_mov_b32_e32 v69, v64
	v_mov_b32_e32 v70, v64
	v_mov_b32_e32 v71, v64
	v_mov_b32_e32 v72, v64
	v_mov_b32_e32 v73, v64
	v_mov_b32_e32 v74, v64
	v_mov_b32_e32 v75, v64
	v_mov_b32_e32 v76, v64
	v_mov_b32_e32 v77, v64
	v_mov_b32_e32 v78, v64
	v_mov_b32_e32 v79, v64
	s_waitcnt lgkmcnt(0)
	v_pk_mul_f32 v[62:63], v[62:63], v[182:183]
	v_pk_mul_f32 v[58:59], v[58:59], v[178:179]
	v_pk_mul_f32 v[54:55], v[54:55], v[174:175]
	v_pk_mul_f32 v[50:51], v[50:51], v[170:171]
	v_pk_mul_f32 v[60:61], v[60:61], v[180:181]
	v_pk_mul_f32 v[56:57], v[56:57], v[176:177]
	v_pk_mul_f32 v[52:53], v[52:53], v[172:173]
	v_pk_mul_f32 v[48:49], v[48:49], v[168:169]
	v_pk_mul_f32 v[46:47], v[46:47], v[182:183]
	v_pk_mul_f32 v[42:43], v[42:43], v[178:179]
	v_pk_mul_f32 v[38:39], v[38:39], v[174:175]
	v_pk_mul_f32 v[34:35], v[34:35], v[170:171]
	v_pk_mul_f32 v[44:45], v[44:45], v[180:181]
	v_pk_mul_f32 v[40:41], v[40:41], v[176:177]
	v_pk_mul_f32 v[36:37], v[36:37], v[172:173]
	v_pk_mul_f32 v[32:33], v[32:33], v[168:169]
	v_pk_mul_f32 v[30:31], v[30:31], v[182:183]
	v_pk_mul_f32 v[26:27], v[26:27], v[178:179]
	v_pk_mul_f32 v[22:23], v[22:23], v[174:175]
	v_pk_mul_f32 v[18:19], v[18:19], v[170:171]
	v_pk_mul_f32 v[28:29], v[28:29], v[180:181]
	v_pk_mul_f32 v[24:25], v[24:25], v[176:177]
	v_pk_mul_f32 v[20:21], v[20:21], v[172:173]
	v_pk_mul_f32 v[16:17], v[16:17], v[168:169]
	v_pk_mul_f32 v[14:15], v[14:15], v[182:183]
	v_pk_mul_f32 v[10:11], v[10:11], v[178:179]
	v_pk_mul_f32 v[6:7], v[6:7], v[174:175]
	v_pk_mul_f32 v[2:3], v[2:3], v[170:171]
	v_pk_mul_f32 v[12:13], v[12:13], v[180:181]
	v_pk_mul_f32 v[8:9], v[8:9], v[176:177]
	v_pk_mul_f32 v[4:5], v[4:5], v[172:173]
	v_pk_mul_f32 v[0:1], v[0:1], v[168:169]

; #define LAS __attribute__((address_space(3)))
; template <int DQK, int DV, bool HAS_BIAS>
; __device__ __forceinline__ void attn_tile(AttnState<DQK, DV>& st, const LAS unsigned char* Kt, const LAS unsigned char* Vt, int bias_mode, const LAS float* tab, int rel0, int nkeys, bool first, LAS float* wsf, int lane) {
;     ...
;     const LAS unsigned char* kp = Kt + q * PK + hi * 16;
;     bf16x8 ka[KS], kb[KS];
; #pragma unroll
;     for (int ks = 0; ks < KS; ++ks) { ka[ks] = *(const LAS bf16x8*)(kp + ks * 32); kb[ks] = *(const LAS bf16x8*)(kp + 32 * PK + ks * 32); }
;     if (HAS_BIAS && bias_mode == 2) {
;         asm volatile("" ::: "memory");
; #pragma unroll
;         for (int r = 0; r < 16; ++r) {
;             const int k = crow(r, hi);
;             const int i0 = min(max(rel0 + k + 128, 0), 191), i1 = min(max(rel0 + k + 160, 0), 191);
;             p0[r] = tab[i0] + st.negm[r]; p1[r] = tab[i1] + st.negm[r];
;         }
;         p0 = __builtin_amdgcn_mfma_f32_32x32x16_bf16(ka[0], st.qf[0], p0, 0, 0, 0);
;         p1 = __builtin_amdgcn_mfma_f32_32x32x16_bf16(kb[0], st.qf[0], p1, 0, 0, 0);
;     } else {
;         p0 = __builtin_amdgcn_mfma_f32_32x32x16_bf16(ka[0], st.qf[0], st.negm, 0, 0, 0);
;         p1 = __builtin_amdgcn_mfma_f32_32x32x16_bf16(kb[0], st.qf[0], st.negm, 0, 0, 0);
;     }
; #pragma unroll
;     for (int ks = 1; ks < KS; ++ks) {
;         p0 = __builtin_amdgcn_mfma_f32_32x32x16_bf16(ka[ks], st.qf[ks], p0, 0, 0, 0);
;         p1 = __builtin_amdgcn_mfma_f32_32x32x16_bf16(kb[ks], st.qf[ks], p1, 0, 0, 0);
;     }
;     const int q4 = (lane & 15) >> 2, blk = (lane >> 4) & 1, pp = lane & 3;
;     const LAS unsigned char* vp = Vt + (4 * hi + q4) * PV + (16 * blk + 4 * pp) * 2;
;     s16x4 vlo[2][4], vhi[2][4];
; #pragma unroll
;     for (int s4 = 0; s4 < 4; ++s4) { vlo[0][s4] = vtr(vp + (16 * s4) * PV); vhi[0][s4] = vtr(vp + (16 * s4 + 8) * PV); }
;     __builtin_amdgcn_sched_barrier(0);
;     if (nkeys < 64) {
; #pragma unroll
;         for (int r = 0; r < 16; ++r) { const int k = crow(r, hi); if (k >= nkeys) p0[r] = -1e30f; if (k + 32 >= nkeys) p1[r] = -1e30f; }
;     }
;     float mxa = __builtin_fmaxf(__builtin_fmaxf(p0[0], p0[1]), p1[0]), mxb = __builtin_fmaxf(__builtin_fmaxf(p0[2], p0[3]), p1[1]);
;     mxa = __builtin_fmaxf(__builtin_fmaxf(mxa, p1[2]), p1[3]);
; #pragma unroll
;     for (int r = 4; r < 16; r += 4) {
.LBB0_580:
	ds_read_b128 v[64:67], v162 offset:8192
	ds_read_b128 v[128:131], v162 offset:8224
	ds_read_b128 v[132:135], v162 offset:14848
	ds_read_b128 v[136:139], v162 offset:14880
	s_cmp_eq_u32 s58, 0
	s_cselect_b64 s[4:5], -1, 0
	s_waitcnt lgkmcnt(3)
	v_mfma_f32_32x32x16_bf16 v[48:63], v[64:67], v[100:103], v[32:47]
	s_cmp_lg_u32 s58, 0
	s_waitcnt lgkmcnt(1)
	v_mfma_f32_32x32x16_bf16 v[64:79], v[132:135], v[100:103], v[32:47]
	v_mfma_f32_32x32x16_bf16 v[48:63], v[128:131], v[80:83], v[48:63]
	ds_read_b128 v[128:131], v162 offset:8256
	ds_read_b128 v[132:135], v162 offset:8288
	s_waitcnt lgkmcnt(2)
	v_mfma_f32_32x32x16_bf16 v[64:79], v[136:139], v[80:83], v[64:79]
	s_waitcnt lgkmcnt(1)
	v_mfma_f32_32x32x16_bf16 v[48:63], v[128:131], v[84:87], v[48:63]
	ds_read_b128 v[128:131], v162 offset:14912
	ds_read_b128 v[136:139], v162 offset:14944
	s_waitcnt lgkmcnt(1)
	v_mfma_f32_32x32x16_bf16 v[64:79], v[128:131], v[84:87], v[64:79]
	v_mfma_f32_32x32x16_bf16 v[48:63], v[132:135], v[88:91], v[48:63]
	ds_read_b128 v[128:131], v162 offset:8320
	ds_read_b128 v[132:135], v162 offset:8352
	s_waitcnt lgkmcnt(2)
	v_mfma_f32_32x32x16_bf16 v[64:79], v[136:139], v[88:91], v[64:79]
	s_waitcnt lgkmcnt(1)
	v_mfma_f32_32x32x16_bf16 v[48:63], v[128:131], v[92:95], v[48:63]
	ds_read_b128 v[128:131], v162 offset:14976
	ds_read_b128 v[164:167], v162 offset:15008
	s_waitcnt lgkmcnt(1)
	v_mfma_f32_32x32x16_bf16 v[64:79], v[128:131], v[92:95], v[64:79]
	v_mfma_f32_32x32x16_bf16 v[48:63], v[132:135], v[96:99], v[48:63]
	ds_read_b64_tr_b16 v[128:129], v163 offset:21504
	ds_read_b64_tr_b16 v[130:131], v163 offset:23040
	ds_read_b64_tr_b16 v[132:133], v163 offset:21568
	ds_read_b64_tr_b16 v[134:135], v163 offset:23104
	ds_read_b64_tr_b16 v[136:137], v163 offset:24576
	ds_read_b64_tr_b16 v[138:139], v163 offset:26112
	ds_read_b64_tr_b16 v[140:141], v163 offset:24640
	ds_read_b64_tr_b16 v[142:143], v163 offset:26176
	s_waitcnt lgkmcnt(8)
	v_mfma_f32_32x32x16_bf16 v[64:79], v[164:167], v[96:99], v[64:79]
	s_nop 1
	v_max_f32_e32 v152, v49, v49
	v_max_f32_e32 v164, v48, v48
	v_max_f32_e32 v152, v164, v152
	s_nop 6
	v_max3_f32 v164, v50, v51, v65
	v_max3_f32 v152, v152, v64, v66
	v_max3_f32 v152, v152, v67, v52
	v_max3_f32 v164, v164, v54, v55
	v_max3_f32 v152, v152, v53, v68
	v_max3_f32 v164, v164, v70, v71
	v_max3_f32 v152, v152, v69, v56
	v_max3_f32 v164, v164, v58, v59
	v_max3_f32 v152, v152, v57, v72
	v_max3_f32 v164, v164, v74, v75
	v_max3_f32 v152, v152, v73, v60
	v_max3_f32 v164, v164, v62, v63
	v_max3_f32 v152, v152, v61, v76
	v_max3_f32 v164, v164, v78, v79
	v_max3_f32 v152, v152, v77, v164
	v_mov_b32_e32 v164, v152
	s_nop 1
	v_permlane32_swap_b32_e32 v152, v164
	v_max_f32_e32 v164, v164, v164
	v_max_f32_e32 v152, v152, v152
	v_max_f32_e32 v152, v152, v164
	s_cbranch_scc0 .Lresc_2
	v_cmp_lt_f32_e32 vcc, s77, v152
	s_cbranch_vccz .LBB0_601
	s_branch .Lresc_2

; __device__ __forceinline__ int crow(int r, int hi) { return (r & 3) + 8 * (r >> 2) + 4 * hi; }
; template <int DQK, int DV, bool HAS_BIAS>
; __device__ __forceinline__ void attn_tile(AttnState<DQK, DV>& st, const LAS unsigned char* Kt, const LAS unsigned char* Vt, int bias_mode, const LAS float* tab, int rel0, int nkeys, bool first, LAS float* wsf, int lane) {
;     ...
;     if (first || __any(mx > ATT_THR)) {
;         const float dl = first ? mx : __builtin_fmaxf(mx, 0.f);
;         st.m += dl;
; #pragma unroll
;         for (int r = 0; r < 16; ++r) { st.negm[r] = -st.m; p0[r] -= dl; p1[r] -= dl; }
;         const float f = __builtin_amdgcn_exp2f(-dl);
;         st.l *= f;
;         if (hi == 0) wsf[q] = f;
; #pragma unroll
;         for (int r = 0; r < 16; ++r) { const float fr = wsf[crow(r, hi)];
; #pragma unroll
;             for (int db = 0; db < NDB; ++db) st.o[db][r] *= fr; }
;     }
.Lresc_2:
	v_max_f32_e32 v32, v152, v152
	v_max_f32_e32 v32, 0, v32
	v_cndmask_b32_e64 v152, v32, v152, s[4:5]
	v_exp_f32_e64 v164, -v152
	s_and_saveexec_b64 s[4:5], s[2:3]
	ds_write_b32 v158, v164 offset:6144
	s_or_b64 exec, exec, s[4:5]
	v_mul_f32_e32 v160, v160, v164
	ds_read_b128 v[164:167], v155 offset:6144
	ds_read_b128 v[168:171], v155 offset:6176
	ds_read_b128 v[172:175], v155 offset:6208
	ds_read_b128 v[176:179], v155 offset:6240
	v_add_f32_e32 v161, v161, v152
	v_xor_b32_e32 v32, 0x80000000, v161
	v_pk_add_f32 v[48:49], v[48:49], v[152:153] op_sel_hi:[1,0] neg_lo:[0,1] neg_hi:[0,1]
	v_pk_add_f32 v[64:65], v[64:65], v[152:153] op_sel_hi:[1,0] neg_lo:[0,1] neg_hi:[0,1]
	v_pk_add_f32 v[50:51], v[50:51], v[152:153] op_sel_hi:[1,0] neg_lo:[0,1] neg_hi:[0,1]
	v_pk_add_f32 v[66:67], v[66:67], v[152:153] op_sel_hi:[1,0] neg_lo:[0,1] neg_hi:[0,1]
	v_pk_add_f32 v[52:53], v[52:53], v[152:153] op_sel_hi:[1,0] neg_lo:[0,1] neg_hi:[0,1]
	v_pk_add_f32 v[68:69], v[68:69], v[152:153] op_sel_hi:[1,0] neg_lo:[0,1] neg_hi:[0,1]
	v_pk_add_f32 v[54:55], v[54:55], v[152:153] op_sel_hi:[1,0] neg_lo:[0,1] neg_hi:[0,1]
	v_pk_add_f32 v[70:71], v[70:71], v[152:153] op_sel_hi:[1,0] neg_lo:[0,1] neg_hi:[0,1]
	v_pk_add_f32 v[56:57], v[56:57], v[152:153] op_sel_hi:[1,0] neg_lo:[0,1] neg_hi:[0,1]
	v_pk_add_f32 v[72:73], v[72:73], v[152:153] op_sel_hi:[1,0] neg_lo:[0,1] neg_hi:[0,1]
	v_pk_add_f32 v[58:59], v[58:59], v[152:153] op_sel_hi:[1,0] neg_lo:[0,1] neg_hi:[0,1]
	v_pk_add_f32 v[74:75], v[74:75], v[152:153] op_sel_hi:[1,0] neg_lo:[0,1] neg_hi:[0,1]
	v_pk_add_f32 v[60:61], v[60:61], v[152:153] op_sel_hi:[1,0] neg_lo:[0,1] neg_hi:[0,1]
	v_pk_add_f32 v[76:77], v[76:77], v[152:153] op_sel_hi:[1,0] neg_lo:[0,1] neg_hi:[0,1]
	v_mov_b32_e32 v33, v32
	v_mov_b32_e32 v34, v32
	v_mov_b32_e32 v35, v32
	v_mov_b32_e32 v36, v32
	v_mov_b32_e32 v37, v32
	v_mov_b32_e32 v38, v32
	v_mov_b32_e32 v39, v32
	v_mov_b32_e32 v40, v32
	v_mov_b32_e32 v41, v32
	v_mov_b32_e32 v42, v32
	v_mov_b32_e32 v43, v32
	v_mov_b32_e32 v44, v32
	v_mov_b32_e32 v45, v32
	v_mov_b32_e32 v46, v32
	v_mov_b32_e32 v47, v32
	v_pk_add_f32 v[62:63], v[62:63], v[152:153] op_sel_hi:[1,0] neg_lo:[0,1] neg_hi:[0,1]
	v_pk_add_f32 v[78:79], v[78:79], v[152:153] op_sel_hi:[1,0] neg_lo:[0,1] neg_hi:[0,1]
	s_waitcnt lgkmcnt(0)
	v_pk_mul_f32 v[30:31], v[30:31], v[178:179]
	v_pk_mul_f32 v[26:27], v[26:27], v[174:175]
	v_pk_mul_f32 v[22:23], v[22:23], v[170:171]
	v_pk_mul_f32 v[18:19], v[18:19], v[166:167]
	v_pk_mul_f32 v[28:29], v[28:29], v[176:177]
	v_pk_mul_f32 v[24:25], v[24:25], v[172:173]
	v_pk_mul_f32 v[20:21], v[20:21], v[168:169]
	v_pk_mul_f32 v[16:17], v[16:17], v[164:165]
	v_pk_mul_f32 v[14:15], v[14:15], v[178:179]
	v_pk_mul_f32 v[10:11], v[10:11], v[174:175]
	v_pk_mul_f32 v[6:7], v[6:7], v[170:171]
	v_pk_mul_f32 v[2:3], v[2:3], v[166:167]
	v_pk_mul_f32 v[12:13], v[12:13], v[176:177]
	v_pk_mul_f32 v[8:9], v[8:9], v[172:173]
	v_pk_mul_f32 v[4:5], v[4:5], v[168:169]
	v_pk_mul_f32 v[0:1], v[0:1], v[164:165]

; __device__ __forceinline__ int crow(int r, int hi) { return (r & 3) + 8 * (r >> 2) + 4 * hi; }
; __device__ __forceinline__ float xmax32(float v) { auto rr = __builtin_amdgcn_permlane32_swap(__float_as_uint(v), __float_as_uint(v), false, false); return fmaxf(__uint_as_float(rr[0]), __uint_as_float(rr[1])); }
; template <int DQK, int DV, bool HAS_BIAS>
; __device__ __forceinline__ void attn_tile(AttnState<DQK, DV>& st, const LAS unsigned char* Kt, const LAS unsigned char* Vt, int bias_mode, const LAS float* tab, int rel0, int nkeys, bool first, LAS float* wsf, int lane) {
;     ...
;     float mxa = __builtin_fmaxf(__builtin_fmaxf(p0[0], p0[1]), p1[0]), mxb = __builtin_fmaxf(__builtin_fmaxf(p0[2], p0[3]), p1[1]);
;     mxa = __builtin_fmaxf(__builtin_fmaxf(mxa, p1[2]), p1[3]);
; #pragma unroll
;     for (int r = 4; r < 16; r += 4) {
;         mxa = __builtin_fmaxf(__builtin_fmaxf(mxa, p0[r]), p0[r + 1]); mxb = __builtin_fmaxf(__builtin_fmaxf(mxb, p0[r + 2]), p0[r + 3]);
;         mxa = __builtin_fmaxf(__builtin_fmaxf(mxa, p1[r]), p1[r + 1]); mxb = __builtin_fmaxf(__builtin_fmaxf(mxb, p1[r + 2]), p1[r + 3]);
;     }
;     const float mx = xmax32(__builtin_fmaxf(mxa, mxb));
;     if (first || __any(mx > ATT_THR)) {
;         const float dl = first ? mx : __builtin_fmaxf(mx, 0.f);
;         st.m += dl;
; #pragma unroll
;         for (int r = 0; r < 16; ++r) { st.negm[r] = -st.m; p0[r] -= dl; p1[r] -= dl; }
;         const float f = __builtin_amdgcn_exp2f(-dl);
;         st.l *= f;
;         if (hi == 0) wsf[q] = f;
; #pragma unroll
;         for (int r = 0; r < 16; ++r) { const float fr = wsf[crow(r, hi)];
; #pragma unroll
;             for (int db = 0; db < NDB; ++db) st.o[db][r] *= fr; }
;     }
.LBB0_620:
	v_max_f32_e32 v121, v49, v49
	v_max_f32_e32 v123, v48, v48
	v_max_f32_e32 v121, v123, v121
	s_nop 6
	v_max3_f32 v123, v50, v51, v65
	v_max3_f32 v121, v121, v64, v66
	v_max3_f32 v121, v121, v67, v52
	v_max3_f32 v123, v123, v54, v55
	v_max3_f32 v121, v121, v53, v68
	v_max3_f32 v123, v123, v70, v71
	v_max3_f32 v121, v121, v69, v56
	v_max3_f32 v123, v123, v58, v59
	v_max3_f32 v121, v121, v57, v72
	v_max3_f32 v123, v123, v74, v75
	v_max3_f32 v121, v121, v73, v60
	v_max3_f32 v123, v123, v62, v63
	v_max3_f32 v121, v121, v61, v76
	v_max3_f32 v123, v123, v78, v79
	v_max3_f32 v121, v121, v77, v123
	v_mov_b32_e32 v123, v121
	s_nop 1
	v_permlane32_swap_b32_e32 v121, v123
	s_cmp_eq_u32 s58, 0
	v_max_f32_e32 v123, v123, v123
	v_max_f32_e32 v121, v121, v121
	s_cselect_b64 s[4:5], -1, 0
	s_cmp_lg_u32 s58, 0
	v_max_f32_e32 v121, v121, v123
	s_cbranch_scc0 .Lresc_3
	v_cmp_lt_f32_e32 vcc, s77, v121
	s_cbranch_vccz .LBB0_615
.Lresc_3:
	v_max_f32_e32 v32, v121, v121
	v_max_f32_e32 v32, 0, v32
	v_cndmask_b32_e64 v32, v32, v121, s[4:5]
	v_exp_f32_e64 v33, -v32
	s_and_saveexec_b64 s[4:5], s[2:3]
	s_cbranch_execz .LBB0_614
	ds_write_b32 v169, v33 offset:6144
	s_branch .LBB0_614

; __device__ __forceinline__ int crow(int r, int hi) { return (r & 3) + 8 * (r >> 2) + 4 * hi; }
; __device__ __forceinline__ float xmax32(float v) { auto rr = __builtin_amdgcn_permlane32_swap(__float_as_uint(v), __float_as_uint(v), false, false); return fmaxf(__uint_as_float(rr[0]), __uint_as_float(rr[1])); }
; template <int DQK, int DV, bool HAS_BIAS>
; __device__ __forceinline__ void attn_tile(AttnState<DQK, DV>& st, const LAS unsigned char* Kt, const LAS unsigned char* Vt, int bias_mode, const LAS float* tab, int rel0, int nkeys, bool first, LAS float* wsf, int lane) {
;     ...
;     float mxa = __builtin_fmaxf(__builtin_fmaxf(p0[0], p0[1]), p1[0]), mxb = __builtin_fmaxf(__builtin_fmaxf(p0[2], p0[3]), p1[1]);
;     mxa = __builtin_fmaxf(__builtin_fmaxf(mxa, p1[2]), p1[3]);
; #pragma unroll
;     for (int r = 4; r < 16; r += 4) {
;         mxa = __builtin_fmaxf(__builtin_fmaxf(mxa, p0[r]), p0[r + 1]); mxb = __builtin_fmaxf(__builtin_fmaxf(mxb, p0[r + 2]), p0[r + 3]);
;         mxa = __builtin_fmaxf(__builtin_fmaxf(mxa, p1[r]), p1[r + 1]); mxb = __builtin_fmaxf(__builtin_fmaxf(mxb, p1[r + 2]), p1[r + 3]);
;     }
;     const float mx = xmax32(__builtin_fmaxf(mxa, mxb));
;     if (first || __any(mx > ATT_THR)) {
;         const float dl = first ? mx : __builtin_fmaxf(mx, 0.f);
;         st.m += dl;
; #pragma unroll
;         for (int r = 0; r < 16; ++r) { st.negm[r] = -st.m; p0[r] -= dl; p1[r] -= dl; }
;         const float f = __builtin_amdgcn_exp2f(-dl);
;         st.l *= f;
;         if (hi == 0) wsf[q] = f;
; #pragma unroll
;         for (int r = 0; r < 16; ++r) { const float fr = wsf[crow(r, hi)];
; #pragma unroll
;             for (int db = 0; db < NDB; ++db) st.o[db][r] *= fr; }
;     }
.LBB0_645:
	s_nop 7
	v_max_f32_e32 v144, v81, v81
	v_max_f32_e32 v145, v80, v80
	v_max_f32_e32 v144, v145, v144
	v_max3_f32 v145, v82, v83, v97
	v_max3_f32 v144, v144, v96, v98
	v_max3_f32 v144, v144, v99, v84
	v_max3_f32 v145, v145, v86, v87
	v_max3_f32 v144, v144, v85, v100
	v_max3_f32 v145, v145, v102, v103
	v_max3_f32 v144, v144, v101, v88
	v_max3_f32 v145, v145, v90, v91
	v_max3_f32 v144, v144, v89, v104
	v_max3_f32 v145, v145, v106, v107
	v_max3_f32 v144, v144, v105, v92
	v_max3_f32 v145, v145, v94, v95
	v_max3_f32 v144, v144, v93, v108
	v_max3_f32 v145, v145, v110, v111
	v_max3_f32 v144, v144, v109, v145
	v_mov_b32_e32 v145, v144
	s_nop 1
	v_permlane32_swap_b32_e32 v144, v145
	s_cmp_eq_u32 s55, 0
	v_max_f32_e32 v145, v145, v145
	v_max_f32_e32 v144, v144, v144
	s_cselect_b64 s[2:3], -1, 0
	s_cmp_lg_u32 s55, 0
	v_max_f32_e32 v144, v144, v145
	s_cbranch_scc0 .Lresc_4
	v_cmp_lt_f32_e32 vcc, s77, v144
	s_cbranch_vccz .LBB0_636
.Lresc_4:
	v_max_f32_e32 v64, v144, v144
	v_max_f32_e32 v64, 0, v64
	v_cndmask_b32_e64 v64, v64, v144, s[2:3]
	v_exp_f32_e64 v65, -v64
	s_and_saveexec_b64 s[2:3], s[0:1]
	s_cbranch_execz .LBB0_635
	ds_write_b32 v192, v65 offset:6144
	s_branch .LBB0_635
